# scan staging writes: loop-invariant LDS addresses kept in registers (on top of v30)
# speedup vs baseline: 1.0066x; 1.0066x over previous
; __device__ __forceinline__ int mk_tid() { int t = (int)threadIdx.x; asm volatile("" : "+v"(t)); return t; }
; #define LAS __attribute__((address_space(3)))
; __device__ __forceinline__ void gla_scan_phase(const Ctx& c, LAS unsigned char* lds) {
;     ...
;         __syncthreads();
;         for (int i = tid; i < 33792 / 16; i += 512) *(LAS u32x4*)(lds + SC_ST + i * 16) = (u32x4){0u, 0u, 0u, 0u};
;         f32x16 sacc[4] = {};
;         { const int c0 = dir ? NCH - 1 : 0; SC_LOAD(c0, mk_tid()); SC_STORE(mk_tid()); SC_LOAD(dir ? NCH - 2 : 1, mk_tid()); }
.LBB0_751:
	s_or_b64 exec, exec, s[0:1]
	v_mov_b32_e32 v45, v200
	s_nop 0
	v_lshlrev_b32_e32 v1, 4, v45
	v_and_b32_e32 v2, 0x1f0, v1
	v_add_u32_e32 v2, 0, v2
	v_ashrrev_i32_e32 v3, 5, v45
	v_mad_u64_u32 v[46:47], s[0:1], v3, s95, v[2:3]
	v_and_b32_e32 v48, 0x70, v1
	s_waitcnt vmcnt(9)
	ds_write_b128 v46, v[36:39]
	v_ashrrev_i32_e32 v36, 3, v45
	v_add_u32_e32 v44, 0, v48
	v_mul_lo_u32 v37, v36, s93
	v_add_u32_e32 v3, v44, v37
	s_waitcnt vmcnt(8)
	ds_write_b128 v3, v[28:31] offset:33792
	v_add_u32_e32 v3, 0x200, v45
	v_ashrrev_i32_e32 v28, 5, v3
	v_mad_u64_u32 v[28:29], s[0:1], v28, s95, v[2:3]
	v_lshrrev_b32_e32 v3, 3, v3
	s_waitcnt vmcnt(7)
	ds_write_b128 v28, v[32:35]
	v_mad_u64_u32 v[28:29], s[0:1], v3, s93, v[44:45]
	v_add_u32_e32 v3, 0x400, v45
	s_waitcnt vmcnt(6)
	ds_write_b128 v28, v[16:19] offset:33792
	v_ashrrev_i32_e32 v16, 5, v3
	v_mad_u64_u32 v[16:17], s[0:1], v16, s95, v[2:3]
	v_lshrrev_b32_e32 v3, 3, v3
	s_waitcnt vmcnt(5)
	ds_write_b128 v16, v[24:27]
	v_mad_u64_u32 v[16:17], s[0:1], v3, s93, v[44:45]
	s_waitcnt vmcnt(4)
	ds_write_b128 v16, v[8:11] offset:33792
	v_add_u32_e32 v8, 0x600, v45
	v_ashrrev_i32_e32 v3, 5, v8
	v_mad_u64_u32 v[2:3], s[0:1], v3, s95, v[2:3]
	s_waitcnt vmcnt(3)
	ds_write_b128 v2, v[20:23]
	v_lshrrev_b32_e32 v2, 3, v8
	v_mad_u64_u32 v[2:3], s[0:1], v2, s93, v[44:45]
	s_waitcnt vmcnt(2)
	ds_write_b128 v2, v[4:7] offset:33792
	v_add3_u32 v2, s96, v37, v48
	s_waitcnt vmcnt(1)
	ds_write_b128 v2, v[12:15]
	v_lshlrev_b32_e32 v2, 1, v45
	v_and_b32_e32 v2, 0x7e, v2
	v_and_b32_e32 v3, 0xffffff8, v36
	v_add_u32_e32 v2, s94, v2
	v_mad_u64_u32 v[4:5], s[0:1], v3, s93, v[2:3]
	v_or_b32_e32 v3, 7, v36
	v_mad_u64_u32 v[2:3], s[0:1], v3, s93, v[2:3]
	v_cmp_gt_i32_e32 vcc, 64, v45
	s_waitcnt vmcnt(0)
	ds_write_b16 v4, v40
	ds_write_b16_d16_hi v4, v40 offset:144
	ds_write_b16 v4, v41 offset:288
	ds_write_b16_d16_hi v4, v41 offset:432
	ds_write_b16 v4, v42 offset:576
	ds_write_b16_d16_hi v4, v42 offset:720
	ds_write_b16 v4, v43 offset:864
	ds_write_b16_d16_hi v2, v43
	s_and_saveexec_b64 s[0:1], vcc
	v_add_u32_e32 v1, 0, v1
	v_add_u32_e32 v1, 0x1e000, v1
	ds_write_b128 v1, v[148:151]
	s_or_b64 exec, exec, s[0:1]
	s_and_b64 s[0:1], s[34:35], exec
	s_cselect_b32 s37, 1, 63
	s_add_u32 s38, s3, s37
	s_addc_u32 s39, s2, 0
	s_lshl_b64 s[0:1], s[38:39], 15
	v_mov_b32_e32 v2, v200
	s_add_u32 s44, s79, s0
	s_addc_u32 s45, s80, s1
	v_ashrrev_i32_e32 v3, 31, v2
	s_add_u32 s0, s81, s0
	v_lshlrev_b64 v[4:5], 4, v[2:3]
	s_addc_u32 s1, s82, s1
	v_lshl_add_u64 v[6:7], s[44:45], 0, v[4:5]
	v_lshl_add_u64 v[8:9], s[0:1], 0, v[4:5]
	global_load_dwordx4 v[152:155], v[6:7], off
	s_mov_b64 vcc, s[20:21]
	s_cbranch_vccz .Lscan_kf_a1
	v_lshrrev_b32_e32 v250, 6, v200
	v_lshlrev_b32_e32 v250, 13, v250
	v_and_b32_e32 v251, 31, v200
	v_lshl_add_u32 v250, v251, 7, v250
	v_bfe_u32 v251, v200, 5, 1
	v_lshl_add_u32 v250, v251, 4, v250
	v_lshlrev_b32_e32 v251, 4, v200
	v_sub_u32_e32 v250, v250, v251
	v_add_u32_e32 v250, 0xffff8800, v250
	v_ashrrev_i32_e32 v251, 31, v250
	v_lshl_add_u64 v[252:253], v[250:251], 0, v[8:9]
	global_load_dwordx4 v[222:225], v[252:253], off offset:-2048
	global_load_dwordx4 v[226:229], v[252:253], off offset:-2016
	global_load_dwordx4 v[230:233], v[252:253], off offset:-1984
	global_load_dwordx4 v[234:237], v[252:253], off offset:-1952
	global_load_dwordx4 v[238:241], v[252:253], off offset:2048
	global_load_dwordx4 v[242:245], v[252:253], off offset:2080
	global_load_dwordx4 v[246:249], v[252:253], off offset:2112
	global_load_dwordx4 v[250:253], v[252:253], off offset:2144
; __device__ __forceinline__ int mk_tid() { int t = (int)threadIdx.x; asm volatile("" : "+v"(t)); return t; }
; __device__ __forceinline__ void gla_scan_phase(const Ctx& c, LAS unsigned char* lds) {
;     ...
;         f32x16 sacc[4] = {};
;         { const int c0 = dir ? NCH - 1 : 0; SC_LOAD(c0, mk_tid()); SC_STORE(mk_tid()); SC_LOAD(dir ? NCH - 2 : 1, mk_tid()); }
;         __syncthreads();
.Lscan_kf_a1:
	v_lshl_add_u64 v[6:7], v[4:5], 0, s[26:27]
	v_lshl_add_u64 v[8:9], s[44:45], 0, v[6:7]
	v_lshl_add_u64 v[6:7], s[0:1], 0, v[6:7]
	global_load_dwordx4 v[160:163], v[8:9], off
	v_lshl_add_u64 v[6:7], v[4:5], 0, s[28:29]
	v_lshl_add_u64 v[8:9], s[44:45], 0, v[6:7]
	v_lshl_add_u64 v[6:7], s[0:1], 0, v[6:7]
	global_load_dwordx4 v[168:171], v[8:9], off
	v_lshl_add_u64 v[6:7], v[4:5], 0, s[30:31]
	v_lshl_add_u64 v[8:9], s[44:45], 0, v[6:7]
	v_lshl_add_u64 v[6:7], s[0:1], 0, v[6:7]
	s_lshl_b64 s[0:1], s[38:39], 13
	s_add_u32 s0, s83, s0
	s_addc_u32 s1, s90, s1
	v_lshl_add_u64 v[4:5], s[0:1], 0, v[4:5]
	s_lshl_b32 s0, s37, 6
	s_sub_i32 s0, s0, 64
	s_lshl_b32 s43, s40, 12
	v_and_or_b32 v1, v2, 63, s0
	v_or_b32_e32 v1, s43, v1
	v_mul_u32_u24_e32 v1, 0x1820, v1
	global_load_dwordx4 v[176:179], v[8:9], off
	v_lshlrev_b32_e32 v6, 1, v1
	v_mov_b32_e32 v7, v0
	v_lshl_add_u64 v[6:7], s[16:17], 0, v[6:7]
	v_ashrrev_i32_e32 v1, 3, v2
	v_lshl_add_u64 v[6:7], v[6:7], 0, s[22:23]
	s_mov_b32 s37, s23
	v_and_b32_e32 v8, -8, v1
	v_lshl_add_u64 v[6:7], v[6:7], 0, s[36:37]
	v_ashrrev_i32_e32 v9, 31, v8
	v_lshl_add_u64 v[6:7], v[8:9], 1, v[6:7]
	v_add_co_u32_e32 v6, vcc, 0x1000, v6
	s_nop 1
	v_addc_co_u32_e32 v7, vcc, 0, v7, vcc
	global_load_dwordx4 v[184:187], v[4:5], off
	global_load_dwordx4 v[188:191], v[6:7], off
	v_cmp_gt_i32_e32 vcc, 64, v2
	s_and_saveexec_b64 s[0:1], vcc
	s_cbranch_execz .LBB0_755
	s_lshl_b64 s[38:39], s[38:39], 10
	s_add_u32 s38, s91, s38
	v_lshlrev_b32_e32 v2, 2, v2
	s_addc_u32 s39, s92, s39
	v_ashrrev_i32_e32 v3, 31, v2
	v_lshl_add_u64 v[2:3], v[2:3], 2, s[38:39]
	global_load_dwordx4 v[148:151], v[2:3], off
.LBB0_755:
	s_or_b64 exec, exec, s[0:1]
	s_and_b64 s[0:1], s[34:35], exec
	s_cselect_b32 s56, 2, -2
	s_lshl_b32 s61, s40, 4
	s_sub_i32 s57, s43, 64
	s_add_i32 s41, s41, s42
	s_add_i32 s58, s61, 0x3fd0
	s_and_b64 s[0:1], s[34:35], exec
	v_readlane_b32 s0, v254, 40
	v_readlane_b32 s1, v254, 30
	v_add_u32_e32 v2, s41, v198
	s_cselect_b32 s0, s17, s0
	s_cselect_b32 s1, s16, s1
	v_mov_b32_e32 v4, s1
	v_mov_b32_e32 v5, s0
	s_movk_i32 s0, 0x800
	v_ashrrev_i32_e32 v3, 31, v2
	v_mov_b32_e32 v14, v0
	v_mov_b32_e32 v15, v0
	s_cselect_b32 s59, 0x1820, s0
	v_lshl_add_u64 v[192:193], v[2:3], 1, v[4:5]
	v_mov_b32_e32 v1, v0
	v_mov_b32_e32 v2, v0
	v_mov_b32_e32 v3, v0
	v_mov_b32_e32 v4, v0
	v_mov_b32_e32 v5, v0
	v_mov_b32_e32 v6, v0
	v_mov_b32_e32 v7, v0
	v_mov_b32_e32 v8, v0
	v_mov_b32_e32 v9, v0
	v_mov_b32_e32 v10, v0
	v_mov_b32_e32 v11, v0
	v_mov_b32_e32 v12, v0
	v_mov_b32_e32 v13, v0
	v_mov_b64_e32 v[30:31], v[14:15]
	v_mov_b64_e32 v[46:47], v[14:15]
	v_mov_b64_e32 v[62:63], v[14:15]
	v_mov_b64_e32 v[78:79], v[14:15]
	s_mov_b32 s60, 0
	s_lshl_b32 s38, s59, 5
	s_mov_b32 s39, s23
	s_mul_i32 s40, s59, 34
	s_mov_b32 s41, s23
	s_mul_i32 s42, s59, 36
	s_mov_b32 s43, s23
	s_mul_i32 s44, s59, 38
	s_mov_b32 s45, s23
	s_mul_i32 s46, s59, 48
	s_mov_b32 s47, s23
	s_mul_i32 s48, s59, 50
	s_mov_b32 s49, s23
	s_mul_i32 s50, s59, 52
	s_mov_b32 s51, s23
	s_mul_i32 s52, s59, 54
	s_mov_b32 s53, s23
	s_bitset1_b32 s61, 14
	s_lshl_b32 s54, s59, 1
	s_mov_b32 s55, s23
	s_mul_i32 s86, s59, 10
	s_mov_b32 s87, s23
	v_mov_b64_e32 v[28:29], v[12:13]
	v_mov_b64_e32 v[26:27], v[10:11]
	v_mov_b64_e32 v[24:25], v[8:9]
	v_mov_b64_e32 v[22:23], v[6:7]
	v_mov_b64_e32 v[20:21], v[4:5]
	v_mov_b64_e32 v[18:19], v[2:3]
	v_mov_b64_e32 v[16:17], v[0:1]
	v_mov_b64_e32 v[44:45], v[12:13]
	v_mov_b64_e32 v[42:43], v[10:11]
	v_mov_b64_e32 v[40:41], v[8:9]
	v_mov_b64_e32 v[38:39], v[6:7]
	v_mov_b64_e32 v[36:37], v[4:5]
	v_mov_b64_e32 v[34:35], v[2:3]
	v_mov_b64_e32 v[32:33], v[0:1]
	v_mov_b64_e32 v[60:61], v[12:13]
	v_mov_b64_e32 v[58:59], v[10:11]
	v_mov_b64_e32 v[56:57], v[8:9]
	v_mov_b64_e32 v[54:55], v[6:7]
	v_mov_b64_e32 v[52:53], v[4:5]
	v_mov_b64_e32 v[50:51], v[2:3]
	v_mov_b64_e32 v[48:49], v[0:1]
	v_mov_b64_e32 v[76:77], v[12:13]
	v_mov_b64_e32 v[74:75], v[10:11]
	v_mov_b64_e32 v[72:73], v[8:9]
	v_mov_b64_e32 v[70:71], v[6:7]
	v_mov_b64_e32 v[68:69], v[4:5]
	v_mov_b64_e32 v[66:67], v[2:3]
	v_mov_b64_e32 v[64:65], v[0:1]
	v_lshrrev_b32_e32 v80, 5, v200
	v_mul_u32_u24_e32 v80, 0x210, v80
	v_lshlrev_b32_e32 v81, 4, v200
	v_and_b32_e32 v81, 0x1f0, v81
	v_add_u32_e32 v156, v80, v81
	v_lshrrev_b32_e32 v80, 3, v200
	v_mul_u32_u24_e32 v81, 0x90, v80
	v_lshlrev_b32_e32 v157, 4, v200
	v_and_b32_e32 v157, 0x70, v157
	v_add_u32_e32 v157, v157, v81
	v_add_u32_e32 v157, 0x11400, v157
	v_and_b32_e32 v80, -8, v80
	v_mul_u32_u24_e32 v80, 0x90, v80
	v_lshlrev_b32_e32 v158, 1, v200
	v_and_b32_e32 v158, 0x7e, v158
	v_add_u32_e32 v158, v158, v80
	v_add_u32_e32 v158, 0x13800, v158
	v_lshlrev_b32_e32 v159, 4, v200
	v_add_u32_e32 v159, 0x1e000, v159
	s_waitcnt lgkmcnt(0)
	s_barrier
	s_branch .LBB0_758

; __device__ __forceinline__ int mk_tid() { int t = (int)threadIdx.x; asm volatile("" : "+v"(t)); return t; }
; __device__ __forceinline__ void gla_scan_phase(const Ctx& c, LAS unsigned char* lds) {
;     ...
;             if (st + 1 < NCH) SC_STORE(mk_tid());
.LBB0_766:
	s_cmp_eq_u32 s60, 64
	s_cbranch_scc1 .LBB0_770
	s_waitcnt vmcnt(0)
	ds_write_b128 v156, v[152:155]
	ds_write_b128 v156, v[160:163] offset:8448
	ds_write_b128 v156, v[168:171] offset:16896
	ds_write_b128 v156, v[176:179] offset:25344
	ds_write_b128 v157, v[184:187]
	ds_write_b16 v158, v188
	ds_write_b16_d16_hi v158, v188 offset:144
	ds_write_b16 v158, v189 offset:288
	ds_write_b16_d16_hi v158, v189 offset:432
	ds_write_b16 v158, v190 offset:576
	ds_write_b16_d16_hi v158, v190 offset:720
	ds_write_b16 v158, v191 offset:864
	ds_write_b16_d16_hi v158, v191 offset:1008
	v_cmp_gt_i32_e32 vcc, 64, v200
	s_and_saveexec_b64 s[0:1], vcc
	ds_write_b128 v159, v[148:151]
	s_or_b64 exec, exec, s[0:1]

; __device__ __forceinline__ void gla_onorm_phase(const Ctx& c, int j) {
;     const bf16_t* P = (const bf16_t*)(c.ws + WS_P); bf16_t* A = (bf16_t*)(c.ws + WS_A);
;     const float* nw = c.gla_o_norm + j * 512;
;     const int gw = blockIdx.x * 8 + c.wave, NGW = c.G * 8;
;     float w8[8];
; #pragma unroll
;     for (int e = 0; e < 8; ++e) w8[e] = nw[c.lane * 8 + e];
;     for (int row = gw; row < MV; row += NGW) {
; #pragma unroll
;         for (int hh = 0; hh < 4; ++hh) {
;             const int col = hh * 512 + c.lane * 8;
;             const u32x4 a = *(const u32x4*)(P + (size_t)row * GLA_NP + col), bq = *(const u32x4*)(A + (size_t)row * DM + col), gq = *(const u32x4*)(P + (size_t)row * GLA_NP + 4096 + col);
;             const unsigned aw[4] = {a.x, a.y, a.z, a.w}, bw[4] = {bq.x, bq.y, bq.z, bq.w}, gw4[4] = {gq.x, gq.y, gq.z, gq.w};
;             float o[8], g[8]; float ss = 0.f;
; #pragma unroll
;             for (int e = 0; e < 4; ++e) {
;                 o[2 * e] = __uint_as_float(aw[e] << 16) + __uint_as_float(bw[e] << 16); o[2 * e + 1] = __uint_as_float(aw[e] & 0xffff0000u) + __uint_as_float(bw[e] & 0xffff0000u);
;                 g[2 * e] = __uint_as_float(gw4[e] << 16); g[2 * e + 1] = __uint_as_float(gw4[e] & 0xffff0000u);
;                 ss += o[2 * e] * o[2 * e] + o[2 * e + 1] * o[2 * e + 1]; }
;             const float rstd = 1.0f / sqrtf(wave_sum(ss) * (1.f / 512.f) + NORM_EPS);
.LBB0_853:
	s_or_b64 exec, exec, s[2:3]
	s_waitcnt lgkmcnt(0)
	s_barrier
	s_nop 0
.LBB0_854:
	s_cmp_lt_i32 s74, 13
	s_cselect_b64 s[0:1], -1, 0
	s_cmp_gt_i32 s75, 12
	s_cselect_b64 s[2:3], -1, 0
	s_and_b64 s[0:1], s[0:1], s[2:3]
	s_andn2_b64 vcc, exec, s[0:1]
	s_cbranch_vccnz .LBB0_912
	v_mov_b32_e32 v8, v200
	s_lshl_b32 s1, s76, 3
	v_readfirstlane_b32 s0, v8
	s_ashr_i32 s0, s0, 6
	s_add_i32 s20, s0, s1
	s_cmpk_gt_i32 s20, 0x403f
	s_cbranch_scc1 .LBB0_858
	v_lshlrev_b32_e32 v0, 5, v8
	v_readlane_b32 s0, v254, 0
	v_and_b32_e32 v9, 0x7e0, v0
	v_readlane_b32 s6, v254, 6
	v_readlane_b32 s7, v254, 7
	s_nop 4
	global_load_dwordx4 v[0:3], v9, s[6:7]
	global_load_dwordx4 v[4:7], v9, s[6:7] offset:16
	v_mbcnt_lo_u32_b32 v9, -1, 0
	v_mbcnt_hi_u32_b32 v9, -1, v9
	v_and_b32_e32 v10, 64, v9
	v_add_u32_e32 v10, 64, v10
	v_xor_b32_e32 v11, 1, v9
	v_cmp_lt_i32_e32 vcc, v11, v10
	v_readlane_b32 s1, v254, 1
	s_ashr_i32 s21, s20, 31
	v_cndmask_b32_e32 v11, v9, v11, vcc
	v_lshlrev_b32_e32 v16, 2, v11
	v_xor_b32_e32 v11, 2, v9
	v_cmp_lt_i32_e32 vcc, v11, v10
	s_lshl_b32 s22, s63, 3
	s_lshl_b64 s[0:1], s[20:21], 12
	v_cndmask_b32_e32 v11, v9, v11, vcc
	v_lshlrev_b32_e32 v17, 2, v11
	v_xor_b32_e32 v11, 4, v9
	v_cmp_lt_i32_e32 vcc, v11, v10
	s_add_u32 s24, s72, s0
	s_addc_u32 s25, s73, s1
	v_cndmask_b32_e32 v11, v9, v11, vcc
	s_waitcnt vmcnt(0)
	v_lshlrev_b32_e32 v18, 2, v11
	v_xor_b32_e32 v11, 8, v9
	v_cmp_lt_i32_e32 vcc, v11, v10
	s_ashr_i32 s23, s22, 31
	s_lshl_b64 s[26:27], s[22:23], 12
	v_cndmask_b32_e32 v11, v9, v11, vcc
	v_lshlrev_b32_e32 v19, 2, v11
	v_xor_b32_e32 v11, 16, v9
	v_cmp_lt_i32_e32 vcc, v11, v10
	s_mul_i32 s1, s20, 0x3040
	v_and_b32_e32 v8, 63, v8
	v_cndmask_b32_e32 v11, v9, v11, vcc
	v_lshlrev_b32_e32 v20, 2, v11
	v_xor_b32_e32 v11, 32, v9
	v_cmp_lt_i32_e32 vcc, v11, v10
	s_mul_hi_i32 s0, s20, 0x3040
	s_add_u32 s28, s72, s1
	v_cndmask_b32_e32 v9, v9, v11, vcc
	v_lshlrev_b32_e32 v21, 2, v9
	v_lshlrev_b32_e32 v8, 4, v8
	v_mov_b32_e32 v9, 0
	s_addc_u32 s29, s73, s0
	s_mul_i32 s0, s63, 0x18200
	s_mul_hi_i32 s1, s22, 0x3040
	v_mov_b32_e32 v22, 0x358637bd
	s_mov_b32 s21, 0xf800000
	v_mov_b32_e32 v23, 0x260
	v_readlane_b32 s2, v254, 2
	v_readlane_b32 s3, v254, 3
	v_readlane_b32 s4, v254, 4
	v_readlane_b32 s5, v254, 5

; __device__ __forceinline__ int mk_tid() { int t = (int)threadIdx.x; asm volatile("" : "+v"(t)); return t; }
; #define LAS __attribute__((address_space(3)))
; __device__ __forceinline__ void gla_scan_phase(const Ctx& c, LAS unsigned char* lds) {
;     ...
;         __syncthreads();
;         for (int i = tid; i < 33792 / 16; i += 512) *(LAS u32x4*)(lds + SC_ST + i * 16) = (u32x4){0u, 0u, 0u, 0u};
;         f32x16 sacc[4] = {};
;         { const int c0 = dir ? NCH - 1 : 0; SC_LOAD(c0, mk_tid()); SC_STORE(mk_tid()); SC_LOAD(dir ? NCH - 2 : 1, mk_tid()); }
.LBB0_1707:
	s_or_b64 exec, exec, s[0:1]
	v_mov_b32_e32 v45, v200
	s_nop 0
	v_lshlrev_b32_e32 v1, 4, v45
	v_and_b32_e32 v2, 0x1f0, v1
	v_add_u32_e32 v2, 0, v2
	v_ashrrev_i32_e32 v3, 5, v45
	v_mad_u64_u32 v[46:47], s[0:1], v3, s81, v[2:3]
	v_and_b32_e32 v48, 0x70, v1
	s_waitcnt vmcnt(9)
	ds_write_b128 v46, v[36:39]
	v_ashrrev_i32_e32 v36, 3, v45
	v_add_u32_e32 v44, 0, v48
	v_mul_lo_u32 v37, v36, s79
	v_add_u32_e32 v3, v44, v37
	s_waitcnt vmcnt(8)
	ds_write_b128 v3, v[28:31] offset:33792
	v_add_u32_e32 v3, 0x200, v45
	v_ashrrev_i32_e32 v28, 5, v3
	v_mad_u64_u32 v[28:29], s[0:1], v28, s81, v[2:3]
	v_lshrrev_b32_e32 v3, 3, v3
	s_waitcnt vmcnt(7)
	ds_write_b128 v28, v[32:35]
	v_mad_u64_u32 v[28:29], s[0:1], v3, s79, v[44:45]
	v_add_u32_e32 v3, 0x400, v45
	s_waitcnt vmcnt(6)
	ds_write_b128 v28, v[16:19] offset:33792
	v_ashrrev_i32_e32 v16, 5, v3
	v_mad_u64_u32 v[16:17], s[0:1], v16, s81, v[2:3]
	v_lshrrev_b32_e32 v3, 3, v3
	s_waitcnt vmcnt(5)
	ds_write_b128 v16, v[24:27]
	v_mad_u64_u32 v[16:17], s[0:1], v3, s79, v[44:45]
	s_waitcnt vmcnt(4)
	ds_write_b128 v16, v[8:11] offset:33792
	v_add_u32_e32 v8, 0x600, v45
	v_ashrrev_i32_e32 v3, 5, v8
	v_mad_u64_u32 v[2:3], s[0:1], v3, s81, v[2:3]
	s_waitcnt vmcnt(3)
	ds_write_b128 v2, v[20:23]
	v_lshrrev_b32_e32 v2, 3, v8
	v_mad_u64_u32 v[2:3], s[0:1], v2, s79, v[44:45]
	s_waitcnt vmcnt(2)
	ds_write_b128 v2, v[4:7] offset:33792
	v_add3_u32 v2, s82, v37, v48
	s_waitcnt vmcnt(1)
	ds_write_b128 v2, v[12:15]
	v_lshlrev_b32_e32 v2, 1, v45
	v_and_b32_e32 v2, 0x7e, v2
	v_and_b32_e32 v3, 0xffffff8, v36
	v_add_u32_e32 v2, s80, v2
	v_mad_u64_u32 v[4:5], s[0:1], v3, s79, v[2:3]
	v_or_b32_e32 v3, 7, v36
	v_mad_u64_u32 v[2:3], s[0:1], v3, s79, v[2:3]
	v_cmp_gt_i32_e32 vcc, 64, v45
	s_waitcnt vmcnt(0)
	ds_write_b16 v4, v40
	ds_write_b16_d16_hi v4, v40 offset:144
	ds_write_b16 v4, v41 offset:288
	ds_write_b16_d16_hi v4, v41 offset:432
	ds_write_b16 v4, v42 offset:576
	ds_write_b16_d16_hi v4, v42 offset:720
	ds_write_b16 v4, v43 offset:864
	ds_write_b16_d16_hi v2, v43
	s_and_saveexec_b64 s[0:1], vcc
	v_add_u32_e32 v1, 0, v1
	v_add_u32_e32 v1, 0x1e000, v1
	ds_write_b128 v1, v[148:151]
	s_or_b64 exec, exec, s[0:1]
	s_and_b64 s[0:1], s[34:35], exec
	s_cselect_b32 s37, 1, 63
	s_add_u32 s38, s59, s37
	s_addc_u32 s39, s58, 0
	s_lshl_b64 s[0:1], s[38:39], 15
	v_mov_b32_e32 v2, v200
	s_add_u32 s44, s65, s0
	s_addc_u32 s45, s66, s1
	v_ashrrev_i32_e32 v3, 31, v2
	s_add_u32 s0, s67, s0
	v_lshlrev_b64 v[4:5], 4, v[2:3]
	s_addc_u32 s1, s68, s1
	v_lshl_add_u64 v[6:7], s[44:45], 0, v[4:5]
	v_lshl_add_u64 v[8:9], s[0:1], 0, v[4:5]
	global_load_dwordx4 v[152:155], v[6:7], off
	s_mov_b64 vcc, s[20:21]
	s_cbranch_vccz .Lscan_kf_b1
	v_lshrrev_b32_e32 v250, 6, v200
	v_lshlrev_b32_e32 v250, 13, v250
	v_and_b32_e32 v251, 31, v200
	v_lshl_add_u32 v250, v251, 7, v250
	v_bfe_u32 v251, v200, 5, 1
	v_lshl_add_u32 v250, v251, 4, v250
	v_lshlrev_b32_e32 v251, 4, v200
	v_sub_u32_e32 v250, v250, v251
	v_add_u32_e32 v250, 0xffff8800, v250
	v_ashrrev_i32_e32 v251, 31, v250
	v_lshl_add_u64 v[252:253], v[250:251], 0, v[8:9]
	global_load_dwordx4 v[222:225], v[252:253], off offset:-2048
	global_load_dwordx4 v[226:229], v[252:253], off offset:-2016
	global_load_dwordx4 v[230:233], v[252:253], off offset:-1984
	global_load_dwordx4 v[234:237], v[252:253], off offset:-1952
	global_load_dwordx4 v[238:241], v[252:253], off offset:2048
	global_load_dwordx4 v[242:245], v[252:253], off offset:2080
	global_load_dwordx4 v[246:249], v[252:253], off offset:2112
	global_load_dwordx4 v[250:253], v[252:253], off offset:2144
; __device__ __forceinline__ int mk_tid() { int t = (int)threadIdx.x; asm volatile("" : "+v"(t)); return t; }
; __device__ __forceinline__ void gla_scan_phase(const Ctx& c, LAS unsigned char* lds) {
;     ...
;         f32x16 sacc[4] = {};
;         { const int c0 = dir ? NCH - 1 : 0; SC_LOAD(c0, mk_tid()); SC_STORE(mk_tid()); SC_LOAD(dir ? NCH - 2 : 1, mk_tid()); }
;         __syncthreads();
.Lscan_kf_b1:
	v_lshl_add_u64 v[6:7], v[4:5], 0, s[26:27]
	v_lshl_add_u64 v[8:9], s[44:45], 0, v[6:7]
	v_lshl_add_u64 v[6:7], s[0:1], 0, v[6:7]
	global_load_dwordx4 v[160:163], v[8:9], off
	v_lshl_add_u64 v[6:7], v[4:5], 0, s[28:29]
	v_lshl_add_u64 v[8:9], s[44:45], 0, v[6:7]
	v_lshl_add_u64 v[6:7], s[0:1], 0, v[6:7]
	global_load_dwordx4 v[168:171], v[8:9], off
	v_lshl_add_u64 v[6:7], v[4:5], 0, s[30:31]
	v_lshl_add_u64 v[8:9], s[44:45], 0, v[6:7]
	v_lshl_add_u64 v[6:7], s[0:1], 0, v[6:7]
	s_lshl_b64 s[0:1], s[38:39], 13
	s_add_u32 s0, s69, s0
	s_addc_u32 s1, s76, s1
	v_lshl_add_u64 v[4:5], s[0:1], 0, v[4:5]
	s_lshl_b32 s0, s37, 6
	s_sub_i32 s0, s0, 64
	s_lshl_b32 s43, s40, 12
	v_and_or_b32 v1, v2, 63, s0
	v_or_b32_e32 v1, s43, v1
	v_mul_u32_u24_e32 v1, 0x1820, v1
	global_load_dwordx4 v[176:179], v[8:9], off
	v_lshlrev_b32_e32 v6, 1, v1
	v_mov_b32_e32 v7, v0
	v_lshl_add_u64 v[6:7], s[16:17], 0, v[6:7]
	v_ashrrev_i32_e32 v1, 3, v2
	v_lshl_add_u64 v[6:7], v[6:7], 0, s[22:23]
	s_mov_b32 s37, s23
	v_and_b32_e32 v8, -8, v1
	v_lshl_add_u64 v[6:7], v[6:7], 0, s[36:37]
	v_ashrrev_i32_e32 v9, 31, v8
	v_lshl_add_u64 v[6:7], v[8:9], 1, v[6:7]
	v_add_co_u32_e32 v6, vcc, 0x1000, v6
	s_nop 1
	v_addc_co_u32_e32 v7, vcc, 0, v7, vcc
	global_load_dwordx4 v[184:187], v[4:5], off
	global_load_dwordx4 v[188:191], v[6:7], off
	v_cmp_gt_i32_e32 vcc, 64, v2
	s_and_saveexec_b64 s[0:1], vcc
	s_cbranch_execz .LBB0_1711
	s_lshl_b64 s[38:39], s[38:39], 10
	s_add_u32 s38, s77, s38
	v_lshlrev_b32_e32 v2, 2, v2
	s_addc_u32 s39, s78, s39
	v_ashrrev_i32_e32 v3, 31, v2
	v_lshl_add_u64 v[2:3], v[2:3], 2, s[38:39]
	global_load_dwordx4 v[148:151], v[2:3], off
.LBB0_1711:
	s_or_b64 exec, exec, s[0:1]
	s_and_b64 s[0:1], s[34:35], exec
	s_cselect_b32 s88, 2, -2
	s_lshl_b32 s93, s40, 4
	s_sub_i32 s89, s43, 64
	s_add_i32 s41, s41, s42
	s_add_i32 s90, s93, 0x3fd0
	s_and_b64 s[0:1], s[34:35], exec
	v_add_u32_e32 v2, s41, v198
	s_cselect_b32 s0, s17, s64
	s_cselect_b32 s1, s16, s33
	v_mov_b32_e32 v4, s1
	v_mov_b32_e32 v5, s0
	s_movk_i32 s0, 0x800
	v_ashrrev_i32_e32 v3, 31, v2
	v_mov_b32_e32 v14, v0
	v_mov_b32_e32 v15, v0
	s_cselect_b32 s91, 0x1820, s0
	v_lshl_add_u64 v[192:193], v[2:3], 1, v[4:5]
	v_mov_b32_e32 v1, v0
	v_mov_b32_e32 v2, v0
	v_mov_b32_e32 v3, v0
	v_mov_b32_e32 v4, v0
	v_mov_b32_e32 v5, v0
	v_mov_b32_e32 v6, v0
	v_mov_b32_e32 v7, v0
	v_mov_b32_e32 v8, v0
	v_mov_b32_e32 v9, v0
	v_mov_b32_e32 v10, v0
	v_mov_b32_e32 v11, v0
	v_mov_b32_e32 v12, v0
	v_mov_b32_e32 v13, v0
	v_mov_b64_e32 v[30:31], v[14:15]
	v_mov_b64_e32 v[46:47], v[14:15]
	v_mov_b64_e32 v[62:63], v[14:15]
	v_mov_b64_e32 v[78:79], v[14:15]
	s_mov_b32 s92, 0
	s_lshl_b32 s38, s91, 5
	s_mov_b32 s39, s23
	s_mul_i32 s40, s91, 34
	s_mov_b32 s41, s23
	s_mul_i32 s42, s91, 36
	s_mov_b32 s43, s23
	s_mul_i32 s44, s91, 38
	s_mov_b32 s45, s23
	s_mul_i32 s46, s91, 48
	s_mov_b32 s47, s23
	s_mul_i32 s48, s91, 50
	s_mov_b32 s49, s23
	s_mul_i32 s50, s91, 52
	s_mov_b32 s51, s23
	s_mul_i32 s52, s91, 54
	s_mov_b32 s53, s23
	s_bitset1_b32 s93, 14
	s_lshl_b32 s54, s91, 1
	s_mov_b32 s55, s23
	s_mul_i32 s56, s91, 10
	s_mov_b32 s57, s23
	v_mov_b64_e32 v[28:29], v[12:13]
	v_mov_b64_e32 v[26:27], v[10:11]
	v_mov_b64_e32 v[24:25], v[8:9]
	v_mov_b64_e32 v[22:23], v[6:7]
	v_mov_b64_e32 v[20:21], v[4:5]
	v_mov_b64_e32 v[18:19], v[2:3]
	v_mov_b64_e32 v[16:17], v[0:1]
	v_mov_b64_e32 v[44:45], v[12:13]
	v_mov_b64_e32 v[42:43], v[10:11]
	v_mov_b64_e32 v[40:41], v[8:9]
	v_mov_b64_e32 v[38:39], v[6:7]
	v_mov_b64_e32 v[36:37], v[4:5]
	v_mov_b64_e32 v[34:35], v[2:3]
	v_mov_b64_e32 v[32:33], v[0:1]
	v_mov_b64_e32 v[60:61], v[12:13]
	v_mov_b64_e32 v[58:59], v[10:11]
	v_mov_b64_e32 v[56:57], v[8:9]
	v_mov_b64_e32 v[54:55], v[6:7]
	v_mov_b64_e32 v[52:53], v[4:5]
	v_mov_b64_e32 v[50:51], v[2:3]
	v_mov_b64_e32 v[48:49], v[0:1]
	v_mov_b64_e32 v[76:77], v[12:13]
	v_mov_b64_e32 v[74:75], v[10:11]
	v_mov_b64_e32 v[72:73], v[8:9]
	v_mov_b64_e32 v[70:71], v[6:7]
	v_mov_b64_e32 v[68:69], v[4:5]
	v_mov_b64_e32 v[66:67], v[2:3]
	v_mov_b64_e32 v[64:65], v[0:1]
	v_lshrrev_b32_e32 v80, 5, v200
	v_mul_u32_u24_e32 v80, 0x210, v80
	v_lshlrev_b32_e32 v81, 4, v200
	v_and_b32_e32 v81, 0x1f0, v81
	v_add_u32_e32 v156, v80, v81
	v_lshrrev_b32_e32 v80, 3, v200
	v_mul_u32_u24_e32 v81, 0x90, v80
	v_lshlrev_b32_e32 v157, 4, v200
	v_and_b32_e32 v157, 0x70, v157
	v_add_u32_e32 v157, v157, v81
	v_add_u32_e32 v157, 0x11400, v157
	v_and_b32_e32 v80, -8, v80
	v_mul_u32_u24_e32 v80, 0x90, v80
	v_lshlrev_b32_e32 v158, 1, v200
	v_and_b32_e32 v158, 0x7e, v158
	v_add_u32_e32 v158, v158, v80
	v_add_u32_e32 v158, 0x13800, v158
	v_lshlrev_b32_e32 v159, 4, v200
	v_add_u32_e32 v159, 0x1e000, v159
	s_waitcnt lgkmcnt(0)
	s_barrier
	s_branch .LBB0_1714

; __device__ __forceinline__ int mk_tid() { int t = (int)threadIdx.x; asm volatile("" : "+v"(t)); return t; }
; __device__ __forceinline__ void gla_scan_phase(const Ctx& c, LAS unsigned char* lds) {
;     ...
;             if (st + 1 < NCH) SC_STORE(mk_tid());
.LBB0_1722:
	s_cmp_eq_u32 s92, 64
	s_cbranch_scc1 .LBB0_1726
	s_waitcnt vmcnt(0)
	ds_write_b128 v156, v[152:155]
	ds_write_b128 v156, v[160:163] offset:8448
	ds_write_b128 v156, v[168:171] offset:16896
	ds_write_b128 v156, v[176:179] offset:25344
	ds_write_b128 v157, v[184:187]
	ds_write_b16 v158, v188
	ds_write_b16_d16_hi v158, v188 offset:144
	ds_write_b16 v158, v189 offset:288
	ds_write_b16_d16_hi v158, v189 offset:432
	ds_write_b16 v158, v190 offset:576
	ds_write_b16_d16_hi v158, v190 offset:720
	ds_write_b16 v158, v191 offset:864
	ds_write_b16_d16_hi v158, v191 offset:1008
	v_cmp_gt_i32_e32 vcc, 64, v200
	s_and_saveexec_b64 s[0:1], vcc
	ds_write_b128 v159, v[148:151]
	s_or_b64 exec, exec, s[0:1]

; __device__ __forceinline__ void xcd_barrier(const XcdBarrier& b) {
;     ...
;     __syncthreads();
.LBB0_1809:
	s_or_b64 exec, exec, s[2:3]
	s_waitcnt lgkmcnt(0)
	s_barrier
	s_nop 0
	s_nop 0
	s_nop 0
	s_nop 0
	s_nop 0
	s_nop 0
	s_nop 0
	s_nop 0
	s_nop 0
	s_nop 0
	s_nop 0
	s_nop 0
	s_nop 0
	s_nop 0
	s_nop 0
